# speedup vs baseline: 1.0336x; 1.0024x over previous
; #define LDA(dst, b, h) for (int m = 0; m < 4; ++m) for (int k = 0; k < 2; ++k) \
;     dst[m][k] = *reinterpret_cast<const bf16x8*>((char*)SA(b, h) + lds_byte(wr * 64 + m * 16 + fr, k * 32 + fq * 8))
; #define LDB(dst, b, h) for (int n = 0; n < 2; ++n) for (int k = 0; k < 2; ++k) \
;     dst[n][k] = *reinterpret_cast<const bf16x8*>((char*)SB(b, h) + lds_byte(wc * 32 + n * 16 + fr, k * 32 + fq * 8))
; #define MMA(ai, bj, At, Bt_) do { __builtin_amdgcn_s_setprio(1); \
;     for (int m = 0; m < 4; ++m) for (int n = 0; n < 2; ++n) for (int k = 0; k < 2; ++k) \
;       acc[ai][bj][m][n] = __builtin_amdgcn_mfma_f32_16x16x32_bf16(Bt_[n][k], At[m][k], acc[ai][bj][m][n], 0, 0, 0); \
;     __builtin_amdgcn_s_setprio(0); } while (0)
; #define WAIT_V(n) asm volatile("s_waitcnt vmcnt(" #n ")" ::: "memory")
; #define WAIT_L(n) asm volatile("s_waitcnt lgkmcnt(" #n ")" ::: "memory")
; #define BAR __builtin_amdgcn_s_barrier()
; #define SCHED __builtin_amdgcn_sched_barrier(0)
; template <int EPI> ...
;     ...
;       LDB(B0, 0, 0); SCHED; LDA(At, 0, 0); STAGE(SA(1, 1), A, brow + HALF, t + 1);
;       WAIT_L(8); BAR; WAIT_L(0); MMA(0, 0, At, B0); BAR; SCHED;
;       LDB(B1, 0, 1); STAGE(SB(0, 0), Bt, bcol, t + 2);
;       BAR; WAIT_L(0); MMA(0, 1, At, B1); BAR;
;       LDA(At, 0, 1); STAGE(SA(0, 0), A, brow, t + 2);
;       BAR; WAIT_L(0); MMA(1, 0, At, B0); BAR; SCHED;
;       STAGE(SB(0, 1), Bt, bcol + HALF, t + 2);
;       WAIT_V(6); BAR; MMA(1, 1, At, B1); BAR;
.LBB0_114:
	s_add_u32 s55, s15, s18
	s_addc_u32 s81, s38, s19
	s_add_u32 s82, s55, 0x104000
	s_addc_u32 s83, s81, 0
	ds_read_b128 v[180:183], v160
	ds_read_b128 v[200:203], v161
	ds_read_b128 v[208:211], v162
	ds_read_b128 v[216:219], v163
	s_add_u32 m0, s32, 0xc000
	s_nop 0
	global_load_lds_dwordx4 v130, s[82:83]
	s_add_u32 m0, s32, 0xe000
	s_nop 0
	global_load_lds_dwordx4 v132, s[82:83]
	s_waitcnt lgkmcnt(4)
	s_barrier
	s_waitcnt lgkmcnt(0)
	s_setprio 1
	s_waitcnt lgkmcnt(0)
	v_mfma_f32_16x16x32_bf16 v[126:129], v[134:137], v[180:183], v[126:129]
	ds_read_b128 v[184:187], v160 offset:1024
	v_mfma_f32_16x16x32_bf16 v[122:125], v[142:145], v[180:183], v[122:125]
	ds_read_b128 v[204:207], v161 offset:1024
	v_mfma_f32_16x16x32_bf16 v[118:121], v[134:137], v[200:203], v[118:121]
	ds_read_b128 v[212:215], v162 offset:1024
	v_mfma_f32_16x16x32_bf16 v[114:117], v[142:145], v[200:203], v[114:117]
	ds_read_b128 v[220:223], v163 offset:1024
	v_mfma_f32_16x16x32_bf16 v[110:113], v[134:137], v[208:211], v[110:113]
	v_mfma_f32_16x16x32_bf16 v[106:109], v[142:145], v[208:211], v[106:109]
	v_mfma_f32_16x16x32_bf16 v[102:105], v[134:137], v[216:219], v[102:105]
	v_mfma_f32_16x16x32_bf16 v[98:101], v[142:145], v[216:219], v[98:101]
	s_waitcnt lgkmcnt(0)
	v_mfma_f32_16x16x32_bf16 v[126:129], v[138:141], v[184:187], v[126:129]
	v_mfma_f32_16x16x32_bf16 v[122:125], v[176:179], v[184:187], v[122:125]
	v_mfma_f32_16x16x32_bf16 v[118:121], v[138:141], v[204:207], v[118:121]
	v_mfma_f32_16x16x32_bf16 v[114:117], v[176:179], v[204:207], v[114:117]
	v_mfma_f32_16x16x32_bf16 v[110:113], v[138:141], v[212:215], v[110:113]
	v_mfma_f32_16x16x32_bf16 v[106:109], v[176:179], v[212:215], v[106:109]
	v_mfma_f32_16x16x32_bf16 v[102:105], v[138:141], v[220:223], v[102:105]
	v_mfma_f32_16x16x32_bf16 v[98:101], v[176:179], v[220:223], v[98:101]
	s_setprio 0
	s_barrier
	s_add_u32 s82, s34, s18
	s_addc_u32 s83, s35, s19
	s_add_u32 s86, s82, 0x8000
	s_addc_u32 s87, s83, 0
	ds_read_b128 v[224:227], v166
	ds_read_b128 v[228:231], v166 offset:1024
	ds_read_b128 v[232:235], v166 offset:2048
	ds_read_b128 v[236:239], v166 offset:3072
	s_add_u32 m0, s32, 0x10000
	s_nop 0
	global_load_lds_dwordx4 v130, s[86:87]
	s_add_u32 m0, s32, 0x12000
	s_nop 0
	global_load_lds_dwordx4 v132, s[86:87]
	s_barrier
	s_waitcnt lgkmcnt(0)
	s_setprio 1
	s_waitcnt lgkmcnt(0)
	v_mfma_f32_16x16x32_bf16 v[86:89], v[224:227], v[180:183], v[86:89]
	v_mfma_f32_16x16x32_bf16 v[70:73], v[232:235], v[180:183], v[70:73]
	v_mfma_f32_16x16x32_bf16 v[54:57], v[224:227], v[200:203], v[54:57]
	v_mfma_f32_16x16x32_bf16 v[50:53], v[232:235], v[200:203], v[50:53]
	v_mfma_f32_16x16x32_bf16 v[46:49], v[224:227], v[208:211], v[46:49]
	v_mfma_f32_16x16x32_bf16 v[42:45], v[232:235], v[208:211], v[42:45]
	v_mfma_f32_16x16x32_bf16 v[38:41], v[224:227], v[216:219], v[38:41]
	v_mfma_f32_16x16x32_bf16 v[34:37], v[232:235], v[216:219], v[34:37]
	v_mfma_f32_16x16x32_bf16 v[86:89], v[228:231], v[184:187], v[86:89]
	v_mfma_f32_16x16x32_bf16 v[70:73], v[236:239], v[184:187], v[70:73]
	v_mfma_f32_16x16x32_bf16 v[54:57], v[228:231], v[204:207], v[54:57]
	v_mfma_f32_16x16x32_bf16 v[50:53], v[236:239], v[204:207], v[50:53]
	v_mfma_f32_16x16x32_bf16 v[46:49], v[228:231], v[212:215], v[46:49]
	v_mfma_f32_16x16x32_bf16 v[42:45], v[236:239], v[212:215], v[42:45]
	v_mfma_f32_16x16x32_bf16 v[38:41], v[228:231], v[220:223], v[38:41]
	v_mfma_f32_16x16x32_bf16 v[34:37], v[236:239], v[220:223], v[34:37]
	s_setprio 0
	s_add_u32 s86, s55, 0x8000
	s_addc_u32 s87, s81, 0
	s_barrier
	ds_read_b128 v[180:183], v160 offset:16384
	ds_read_b128 v[200:203], v161 offset:16384
	ds_read_b128 v[208:211], v162 offset:16384
	ds_read_b128 v[216:219], v163 offset:16384
	s_add_u32 m0, s32, 0x0
	s_nop 0
	global_load_lds_dwordx4 v130, s[86:87]
	s_add_u32 m0, s32, 0x2000
	s_nop 0
	global_load_lds_dwordx4 v132, s[86:87]
	s_waitcnt vmcnt(10)
	s_barrier
	s_waitcnt lgkmcnt(0)
	s_setprio 1
	s_waitcnt lgkmcnt(0)
	v_mfma_f32_16x16x32_bf16 v[30:33], v[134:137], v[180:183], v[30:33]
	ds_read_b128 v[184:187], v160 offset:17408
	v_mfma_f32_16x16x32_bf16 v[26:29], v[142:145], v[180:183], v[26:29]
	ds_read_b128 v[204:207], v161 offset:17408
	v_mfma_f32_16x16x32_bf16 v[22:25], v[134:137], v[200:203], v[22:25]
	ds_read_b128 v[212:215], v162 offset:17408
	v_mfma_f32_16x16x32_bf16 v[18:21], v[142:145], v[200:203], v[18:21]
	ds_read_b128 v[220:223], v163 offset:17408
	v_mfma_f32_16x16x32_bf16 v[14:17], v[134:137], v[208:211], v[14:17]
	v_mfma_f32_16x16x32_bf16 v[10:13], v[142:145], v[208:211], v[10:13]
	v_mfma_f32_16x16x32_bf16 v[6:9], v[134:137], v[216:219], v[6:9]
	v_mfma_f32_16x16x32_bf16 v[2:5], v[142:145], v[216:219], v[2:5]
	s_waitcnt lgkmcnt(0)
	v_mfma_f32_16x16x32_bf16 v[30:33], v[138:141], v[184:187], v[30:33]
	v_mfma_f32_16x16x32_bf16 v[26:29], v[176:179], v[184:187], v[26:29]
	v_mfma_f32_16x16x32_bf16 v[22:25], v[138:141], v[204:207], v[22:25]
	v_mfma_f32_16x16x32_bf16 v[18:21], v[176:179], v[204:207], v[18:21]
	v_mfma_f32_16x16x32_bf16 v[14:17], v[138:141], v[212:215], v[14:17]
	v_mfma_f32_16x16x32_bf16 v[10:13], v[176:179], v[212:215], v[10:13]
	v_mfma_f32_16x16x32_bf16 v[6:9], v[138:141], v[220:223], v[6:9]
	v_mfma_f32_16x16x32_bf16 v[2:5], v[176:179], v[220:223], v[2:5]
	s_setprio 0
	s_barrier
	ds_read_b128 v[134:137], v167
	ds_read_b128 v[138:141], v167 offset:1024
	ds_read_b128 v[142:145], v167 offset:2048
	ds_read_b128 v[176:179], v167 offset:3072
	s_add_u32 s86, s82, 0x108000
	s_addc_u32 s87, s83, 0
	s_add_u32 m0, s32, 0x14000
	s_nop 0
	global_load_lds_dwordx4 v130, s[86:87]
	s_add_u32 m0, s32, 0x16000
	s_nop 0
	global_load_lds_dwordx4 v132, s[86:87]
	s_waitcnt vmcnt(6)
	s_barrier
; #define LDA(dst, b, h) for (int m = 0; m < 4; ++m) for (int k = 0; k < 2; ++k) \
;     dst[m][k] = *reinterpret_cast<const bf16x8*>((char*)SA(b, h) + lds_byte(wr * 64 + m * 16 + fr, k * 32 + fq * 8))
; #define LDB(dst, b, h) for (int n = 0; n < 2; ++n) for (int k = 0; k < 2; ++k) \
;     dst[n][k] = *reinterpret_cast<const bf16x8*>((char*)SB(b, h) + lds_byte(wc * 32 + n * 16 + fr, k * 32 + fq * 8))
; #define MMA(ai, bj, At, Bt_) do { __builtin_amdgcn_s_setprio(1); \
;     for (int m = 0; m < 4; ++m) for (int n = 0; n < 2; ++n) for (int k = 0; k < 2; ++k) \
;       acc[ai][bj][m][n] = __builtin_amdgcn_mfma_f32_16x16x32_bf16(Bt_[n][k], At[m][k], acc[ai][bj][m][n], 0, 0, 0); \
;     __builtin_amdgcn_s_setprio(0); } while (0)
; #define WAIT_V(n) asm volatile("s_waitcnt vmcnt(" #n ")" ::: "memory")
; #define WAIT_L(n) asm volatile("s_waitcnt lgkmcnt(" #n ")" ::: "memory")
; #define BAR __builtin_amdgcn_s_barrier()
; #define SCHED __builtin_amdgcn_sched_barrier(0)
; template <int EPI> ...
;     ...
;       WAIT_V(6); BAR; MMA(1, 1, At, B1); BAR;
;       LDB(B0, 1, 0); SCHED; LDA(At, 1, 0); STAGE(SA(0, 1), A, brow + HALF, t + 2);
;       WAIT_L(8); BAR; WAIT_L(0); MMA(0, 0, At, B0); BAR; SCHED;
;       LDB(B1, 1, 1); STAGE(SB(1, 0), Bt, bcol, t + 3);
;       BAR; WAIT_L(0); MMA(0, 1, At, B1); BAR;
;       LDA(At, 1, 1); STAGE(SA(1, 0), A, brow, t + 3);
	s_setprio 1
	v_mfma_f32_16x16x32_bf16 v[58:61], v[224:227], v[180:183], v[58:61]
	v_mfma_f32_16x16x32_bf16 v[62:65], v[232:235], v[180:183], v[62:65]
	v_mfma_f32_16x16x32_bf16 v[66:69], v[224:227], v[200:203], v[66:69]
	v_mfma_f32_16x16x32_bf16 v[74:77], v[232:235], v[200:203], v[74:77]
	v_mfma_f32_16x16x32_bf16 v[78:81], v[224:227], v[208:211], v[78:81]
	v_mfma_f32_16x16x32_bf16 v[82:85], v[232:235], v[208:211], v[82:85]
	v_mfma_f32_16x16x32_bf16 v[90:93], v[224:227], v[216:219], v[90:93]
	v_mfma_f32_16x16x32_bf16 v[94:97], v[232:235], v[216:219], v[94:97]
	v_mfma_f32_16x16x32_bf16 v[58:61], v[228:231], v[184:187], v[58:61]
	v_mfma_f32_16x16x32_bf16 v[62:65], v[236:239], v[184:187], v[62:65]
	v_mfma_f32_16x16x32_bf16 v[66:69], v[228:231], v[204:207], v[66:69]
	v_mfma_f32_16x16x32_bf16 v[74:77], v[236:239], v[204:207], v[74:77]
	v_mfma_f32_16x16x32_bf16 v[78:81], v[228:231], v[212:215], v[78:81]
	v_mfma_f32_16x16x32_bf16 v[82:85], v[236:239], v[212:215], v[82:85]
	v_mfma_f32_16x16x32_bf16 v[90:93], v[228:231], v[220:223], v[90:93]
	v_mfma_f32_16x16x32_bf16 v[94:97], v[236:239], v[220:223], v[94:97]
	s_setprio 0
	s_barrier
	s_add_u32 s86, s55, 0x108000
	s_addc_u32 s87, s81, 0
	ds_read_b128 v[180:183], v160 offset:32768
	ds_read_b128 v[200:203], v161 offset:32768
	ds_read_b128 v[208:211], v162 offset:32768
	ds_read_b128 v[216:219], v163 offset:32768
	s_add_u32 m0, s32, 0x4000
	s_nop 0
	global_load_lds_dwordx4 v130, s[86:87]
	s_add_u32 m0, s32, 0x6000
	s_nop 0
	global_load_lds_dwordx4 v132, s[86:87]
	s_waitcnt lgkmcnt(4)
	s_barrier
	s_waitcnt lgkmcnt(0)
	s_setprio 1
	s_waitcnt lgkmcnt(0)
	v_mfma_f32_16x16x32_bf16 v[126:129], v[134:137], v[180:183], v[126:129]
	ds_read_b128 v[184:187], v160 offset:33792
	v_mfma_f32_16x16x32_bf16 v[122:125], v[142:145], v[180:183], v[122:125]
	ds_read_b128 v[204:207], v161 offset:33792
	v_mfma_f32_16x16x32_bf16 v[118:121], v[134:137], v[200:203], v[118:121]
	ds_read_b128 v[212:215], v162 offset:33792
	v_mfma_f32_16x16x32_bf16 v[114:117], v[142:145], v[200:203], v[114:117]
	ds_read_b128 v[220:223], v163 offset:33792
	v_mfma_f32_16x16x32_bf16 v[110:113], v[134:137], v[208:211], v[110:113]
	v_mfma_f32_16x16x32_bf16 v[106:109], v[142:145], v[208:211], v[106:109]
	v_mfma_f32_16x16x32_bf16 v[102:105], v[134:137], v[216:219], v[102:105]
	v_mfma_f32_16x16x32_bf16 v[98:101], v[142:145], v[216:219], v[98:101]
	s_waitcnt lgkmcnt(0)
	v_mfma_f32_16x16x32_bf16 v[126:129], v[138:141], v[184:187], v[126:129]
	v_mfma_f32_16x16x32_bf16 v[122:125], v[176:179], v[184:187], v[122:125]
	v_mfma_f32_16x16x32_bf16 v[118:121], v[138:141], v[204:207], v[118:121]
	v_mfma_f32_16x16x32_bf16 v[114:117], v[176:179], v[204:207], v[114:117]
	v_mfma_f32_16x16x32_bf16 v[110:113], v[138:141], v[212:215], v[110:113]
	v_mfma_f32_16x16x32_bf16 v[106:109], v[176:179], v[212:215], v[106:109]
	v_mfma_f32_16x16x32_bf16 v[102:105], v[138:141], v[220:223], v[102:105]
	v_mfma_f32_16x16x32_bf16 v[98:101], v[176:179], v[220:223], v[98:101]
	s_setprio 0
	s_barrier
	s_add_u32 s86, s82, 0xc000
	s_addc_u32 s87, s83, 0
	ds_read_b128 v[224:227], v168
	ds_read_b128 v[228:231], v168 offset:1024
	ds_read_b128 v[232:235], v168 offset:2048
	ds_read_b128 v[236:239], v168 offset:3072
	s_add_u32 m0, s32, 0x18000
	s_nop 0
	global_load_lds_dwordx4 v130, s[86:87]
	s_add_u32 m0, s32, 0x1a000
	s_nop 0
	global_load_lds_dwordx4 v132, s[86:87]
	s_barrier
	s_waitcnt lgkmcnt(0)
	s_setprio 1
	s_waitcnt lgkmcnt(0)
	v_mfma_f32_16x16x32_bf16 v[86:89], v[224:227], v[180:183], v[86:89]
	v_mfma_f32_16x16x32_bf16 v[70:73], v[232:235], v[180:183], v[70:73]
	v_mfma_f32_16x16x32_bf16 v[54:57], v[224:227], v[200:203], v[54:57]
	v_mfma_f32_16x16x32_bf16 v[50:53], v[232:235], v[200:203], v[50:53]
	v_mfma_f32_16x16x32_bf16 v[46:49], v[224:227], v[208:211], v[46:49]
	v_mfma_f32_16x16x32_bf16 v[42:45], v[232:235], v[208:211], v[42:45]
	v_mfma_f32_16x16x32_bf16 v[38:41], v[224:227], v[216:219], v[38:41]
	v_mfma_f32_16x16x32_bf16 v[34:37], v[232:235], v[216:219], v[34:37]
	v_mfma_f32_16x16x32_bf16 v[86:89], v[228:231], v[184:187], v[86:89]
	v_mfma_f32_16x16x32_bf16 v[70:73], v[236:239], v[184:187], v[70:73]
	v_mfma_f32_16x16x32_bf16 v[54:57], v[228:231], v[204:207], v[54:57]
	v_mfma_f32_16x16x32_bf16 v[50:53], v[236:239], v[204:207], v[50:53]
	v_mfma_f32_16x16x32_bf16 v[46:49], v[228:231], v[212:215], v[46:49]
	v_mfma_f32_16x16x32_bf16 v[42:45], v[236:239], v[212:215], v[42:45]
	v_mfma_f32_16x16x32_bf16 v[38:41], v[228:231], v[220:223], v[38:41]
	v_mfma_f32_16x16x32_bf16 v[34:37], v[236:239], v[220:223], v[34:37]
	s_setprio 0
	s_add_u32 s86, s55, 0xc000
	s_addc_u32 s87, s81, 0
	s_barrier
	ds_read_b128 v[180:183], v160 offset:49152
	ds_read_b128 v[200:203], v161 offset:49152
	ds_read_b128 v[208:211], v162 offset:49152
	ds_read_b128 v[216:219], v163 offset:49152
	s_add_u32 m0, s32, 0x8000
	s_nop 0
	global_load_lds_dwordx4 v130, s[86:87]
	s_add_u32 m0, s32, 0xa000
	s_nop 0
	global_load_lds_dwordx4 v132, s[86:87]
	s_waitcnt vmcnt(10)
	s_barrier
; #define LDA(dst, b, h) for (int m = 0; m < 4; ++m) for (int k = 0; k < 2; ++k) \
;     dst[m][k] = *reinterpret_cast<const bf16x8*>((char*)SA(b, h) + lds_byte(wr * 64 + m * 16 + fr, k * 32 + fq * 8))
; #define LDB(dst, b, h) for (int n = 0; n < 2; ++n) for (int k = 0; k < 2; ++k) \
;     dst[n][k] = *reinterpret_cast<const bf16x8*>((char*)SB(b, h) + lds_byte(wc * 32 + n * 16 + fr, k * 32 + fq * 8))
; #define MMA(ai, bj, At, Bt_) do { __builtin_amdgcn_s_setprio(1); \
;     for (int m = 0; m < 4; ++m) for (int n = 0; n < 2; ++n) for (int k = 0; k < 2; ++k) \
;       acc[ai][bj][m][n] = __builtin_amdgcn_mfma_f32_16x16x32_bf16(Bt_[n][k], At[m][k], acc[ai][bj][m][n], 0, 0, 0); \
;     __builtin_amdgcn_s_setprio(0); } while (0)
; #define WAIT_V(n) asm volatile("s_waitcnt vmcnt(" #n ")" ::: "memory")
; #define WAIT_L(n) asm volatile("s_waitcnt lgkmcnt(" #n ")" ::: "memory")
; #define BAR __builtin_amdgcn_s_barrier()
; #define SCHED __builtin_amdgcn_sched_barrier(0)
; template <int EPI> ...
;     ...
;       BAR; WAIT_L(0); MMA(1, 0, At, B0); BAR; SCHED;
;       STAGE(SB(1, 1), Bt, bcol + HALF, t + 3);
;       WAIT_V(6); BAR; MMA(1, 1, At, B1); BAR;
;     }
;     { LDB(B0, 0, 0); LDA(At, 0, 0); STAGE(SA(1, 1), A, brow + HALF, nt - 1);
;       BAR; WAIT_L(0); MMA(0, 0, At, B0); BAR;
;       LDB(B1, 0, 1); BAR; WAIT_L(0); MMA(0, 1, At, B1); BAR;
	s_waitcnt lgkmcnt(0)
	s_setprio 1
	s_waitcnt lgkmcnt(0)
	v_mfma_f32_16x16x32_bf16 v[30:33], v[134:137], v[180:183], v[30:33]
	ds_read_b128 v[184:187], v160 offset:50176
	v_mfma_f32_16x16x32_bf16 v[26:29], v[142:145], v[180:183], v[26:29]
	ds_read_b128 v[204:207], v161 offset:50176
	v_mfma_f32_16x16x32_bf16 v[22:25], v[134:137], v[200:203], v[22:25]
	ds_read_b128 v[212:215], v162 offset:50176
	v_mfma_f32_16x16x32_bf16 v[18:21], v[142:145], v[200:203], v[18:21]
	ds_read_b128 v[220:223], v163 offset:50176
	v_mfma_f32_16x16x32_bf16 v[14:17], v[134:137], v[208:211], v[14:17]
	v_mfma_f32_16x16x32_bf16 v[10:13], v[142:145], v[208:211], v[10:13]
	v_mfma_f32_16x16x32_bf16 v[6:9], v[134:137], v[216:219], v[6:9]
	v_mfma_f32_16x16x32_bf16 v[2:5], v[142:145], v[216:219], v[2:5]
	s_waitcnt lgkmcnt(0)
	v_mfma_f32_16x16x32_bf16 v[30:33], v[138:141], v[184:187], v[30:33]
	v_mfma_f32_16x16x32_bf16 v[26:29], v[176:179], v[184:187], v[26:29]
	v_mfma_f32_16x16x32_bf16 v[22:25], v[138:141], v[204:207], v[22:25]
	v_mfma_f32_16x16x32_bf16 v[18:21], v[176:179], v[204:207], v[18:21]
	v_mfma_f32_16x16x32_bf16 v[14:17], v[138:141], v[212:215], v[14:17]
	v_mfma_f32_16x16x32_bf16 v[10:13], v[176:179], v[212:215], v[10:13]
	v_mfma_f32_16x16x32_bf16 v[6:9], v[138:141], v[220:223], v[6:9]
	v_mfma_f32_16x16x32_bf16 v[2:5], v[176:179], v[220:223], v[2:5]
	s_setprio 0
	s_barrier
	ds_read_b128 v[134:137], v159
	ds_read_b128 v[138:141], v159 offset:1024
	ds_read_b128 v[142:145], v159 offset:2048
	ds_read_b128 v[176:179], v159 offset:3072
	s_add_u32 s82, s82, 0x10c000
	s_addc_u32 s83, s83, 0
	s_add_u32 m0, s32, 0x1c000
	s_nop 0
	global_load_lds_dwordx4 v130, s[82:83]
	s_add_u32 m0, s32, 0x1e000
	s_nop 0
	global_load_lds_dwordx4 v132, s[82:83]
	s_waitcnt vmcnt(6)
	s_barrier
	s_setprio 1
	v_mfma_f32_16x16x32_bf16 v[58:61], v[224:227], v[180:183], v[58:61]
	v_mfma_f32_16x16x32_bf16 v[62:65], v[232:235], v[180:183], v[62:65]
	v_mfma_f32_16x16x32_bf16 v[66:69], v[224:227], v[200:203], v[66:69]
	v_mfma_f32_16x16x32_bf16 v[74:77], v[232:235], v[200:203], v[74:77]
	v_mfma_f32_16x16x32_bf16 v[78:81], v[224:227], v[208:211], v[78:81]
	v_mfma_f32_16x16x32_bf16 v[82:85], v[232:235], v[208:211], v[82:85]
	v_mfma_f32_16x16x32_bf16 v[90:93], v[224:227], v[216:219], v[90:93]
	v_mfma_f32_16x16x32_bf16 v[94:97], v[232:235], v[216:219], v[94:97]
	v_mfma_f32_16x16x32_bf16 v[58:61], v[228:231], v[184:187], v[58:61]
	v_mfma_f32_16x16x32_bf16 v[62:65], v[236:239], v[184:187], v[62:65]
	v_mfma_f32_16x16x32_bf16 v[66:69], v[228:231], v[204:207], v[66:69]
	v_mfma_f32_16x16x32_bf16 v[74:77], v[236:239], v[204:207], v[74:77]
	v_mfma_f32_16x16x32_bf16 v[78:81], v[228:231], v[212:215], v[78:81]
	v_mfma_f32_16x16x32_bf16 v[82:85], v[236:239], v[212:215], v[82:85]
	v_mfma_f32_16x16x32_bf16 v[90:93], v[228:231], v[220:223], v[90:93]
	v_mfma_f32_16x16x32_bf16 v[94:97], v[236:239], v[220:223], v[94:97]
	s_setprio 0
	s_add_i32 s39, s39, 2
	s_add_u32 s18, s18, 0x8000
	s_addc_u32 s19, s19, 0
	s_cmp_lt_u32 s39, 60
	s_barrier
	s_cbranch_scc1 .LBB0_114
	s_or_b32 s14, s14, 1
	s_ashr_i32 s15, s14, 31
	s_lshl_b64 s[14:15], s[14:15], 20
	s_add_u32 s14, s16, s14
	s_addc_u32 s15, s17, s15
	s_add_u32 s14, s14, 0xfc000
	s_addc_u32 s15, s15, 0
	v_readfirstlane_b32 s18, v164
	ds_read_b128 v[134:137], v159
	ds_read_b128 v[138:141], v159 offset:1024
	ds_read_b128 v[142:145], v159 offset:2048
	ds_read_b128 v[176:179], v159 offset:3072
	ds_read_b128 v[180:183], v160
	ds_read_b128 v[184:187], v160 offset:1024
	ds_read_b128 v[200:203], v161
	ds_read_b128 v[204:207], v161 offset:1024
	ds_read_b128 v[208:211], v162
	ds_read_b128 v[212:215], v162 offset:1024
	ds_read_b128 v[216:219], v163
	ds_read_b128 v[220:223], v163 offset:1024
	s_mov_b32 m0, s18
	v_lshl_add_u64 v[146:147], s[14:15], 0, v[130:131]
	global_load_lds_dwordx4 v[146:147], off
	v_lshl_add_u64 v[146:147], s[14:15], 0, v[132:133]
	v_readfirstlane_b32 s14, v165
	s_mov_b32 m0, s14
	s_nop 0
	global_load_lds_dwordx4 v[146:147], off
	s_barrier
	s_waitcnt lgkmcnt(0)
	s_setprio 1
	s_waitcnt lgkmcnt(0)
	v_mfma_f32_16x16x32_bf16 v[126:129], v[134:137], v[180:183], v[126:129]
	v_mfma_f32_16x16x32_bf16 v[122:125], v[142:145], v[180:183], v[122:125]
	v_mfma_f32_16x16x32_bf16 v[110:113], v[134:137], v[208:211], v[110:113]
	v_mfma_f32_16x16x32_bf16 v[106:109], v[142:145], v[208:211], v[106:109]
	v_mfma_f32_16x16x32_bf16 v[126:129], v[138:141], v[184:187], v[126:129]
	v_mfma_f32_16x16x32_bf16 v[122:125], v[176:179], v[184:187], v[122:125]
	v_mfma_f32_16x16x32_bf16 v[118:121], v[134:137], v[200:203], v[118:121]
	v_mfma_f32_16x16x32_bf16 v[114:117], v[142:145], v[200:203], v[114:117]
	v_mfma_f32_16x16x32_bf16 v[110:113], v[138:141], v[212:215], v[110:113]
	v_mfma_f32_16x16x32_bf16 v[106:109], v[176:179], v[212:215], v[106:109]
	v_mfma_f32_16x16x32_bf16 v[102:105], v[134:137], v[216:219], v[102:105]
	v_mfma_f32_16x16x32_bf16 v[98:101], v[142:145], v[216:219], v[98:101]
	v_mfma_f32_16x16x32_bf16 v[224:227], v[138:141], v[204:207], v[118:121]
	v_mfma_f32_16x16x32_bf16 v[228:231], v[176:179], v[204:207], v[114:117]
	v_mfma_f32_16x16x32_bf16 v[232:235], v[138:141], v[220:223], v[102:105]
	v_mfma_f32_16x16x32_bf16 v[236:239], v[176:179], v[220:223], v[98:101]
	s_setprio 0
	s_barrier
	s_nop 1
	ds_read_b128 v[98:101], v166
	ds_read_b128 v[102:105], v166 offset:1024
	ds_read_b128 v[114:117], v166 offset:2048
	ds_read_b128 v[118:121], v166 offset:3072
	s_barrier
; #define LDA(dst, b, h) for (int m = 0; m < 4; ++m) for (int k = 0; k < 2; ++k) \
;     dst[m][k] = *reinterpret_cast<const bf16x8*>((char*)SA(b, h) + lds_byte(wr * 64 + m * 16 + fr, k * 32 + fq * 8))
; #define LDB(dst, b, h) for (int n = 0; n < 2; ++n) for (int k = 0; k < 2; ++k) \
;     dst[n][k] = *reinterpret_cast<const bf16x8*>((char*)SB(b, h) + lds_byte(wc * 32 + n * 16 + fr, k * 32 + fq * 8))
; #define MMA(ai, bj, At, Bt_) do { __builtin_amdgcn_s_setprio(1); \
;     for (int m = 0; m < 4; ++m) for (int n = 0; n < 2; ++n) for (int k = 0; k < 2; ++k) \
;       acc[ai][bj][m][n] = __builtin_amdgcn_mfma_f32_16x16x32_bf16(Bt_[n][k], At[m][k], acc[ai][bj][m][n], 0, 0, 0); \
;     __builtin_amdgcn_s_setprio(0); } while (0)
; #define WAIT_V(n) asm volatile("s_waitcnt vmcnt(" #n ")" ::: "memory")
; #define WAIT_L(n) asm volatile("s_waitcnt lgkmcnt(" #n ")" ::: "memory")
; #define BAR __builtin_amdgcn_s_barrier()
; template <int EPI> ...
;     ...
;       LDB(B1, 0, 1); BAR; WAIT_L(0); MMA(0, 1, At, B1); BAR;
;       LDA(At, 0, 1); WAIT_V(4); BAR; WAIT_L(0); MMA(1, 0, At, B0); MMA(1, 1, At, B1); BAR; }
;     { LDB(B0, 1, 0); LDA(At, 1, 0); WAIT_V(2); BAR; WAIT_L(0); MMA(0, 0, At, B0); BAR;
	s_waitcnt lgkmcnt(0)
	s_setprio 1
	s_waitcnt lgkmcnt(0)
	v_mfma_f32_16x16x32_bf16 v[70:73], v[114:117], v[180:183], v[70:73]
	v_mfma_f32_16x16x32_bf16 v[46:49], v[98:101], v[208:211], v[46:49]
	v_mfma_f32_16x16x32_bf16 v[42:45], v[114:117], v[208:211], v[42:45]
	v_mfma_f32_16x16x32_bf16 v[38:41], v[98:101], v[216:219], v[38:41]
	v_mfma_f32_16x16x32_bf16 v[34:37], v[114:117], v[216:219], v[34:37]
	v_mfma_f32_16x16x32_bf16 v[86:89], v[98:101], v[180:183], v[86:89]
	v_mfma_f32_16x16x32_bf16 v[70:73], v[118:121], v[184:187], v[70:73]
	v_mfma_f32_16x16x32_bf16 v[54:57], v[98:101], v[200:203], v[54:57]
	v_mfma_f32_16x16x32_bf16 v[50:53], v[114:117], v[200:203], v[50:53]
	v_mfma_f32_16x16x32_bf16 v[46:49], v[102:105], v[212:215], v[46:49]
	v_mfma_f32_16x16x32_bf16 v[42:45], v[118:121], v[212:215], v[42:45]
	v_mfma_f32_16x16x32_bf16 v[38:41], v[102:105], v[220:223], v[38:41]
	v_mfma_f32_16x16x32_bf16 v[34:37], v[118:121], v[220:223], v[34:37]
	v_mfma_f32_16x16x32_bf16 v[240:243], v[102:105], v[184:187], v[86:89]
	v_mfma_f32_16x16x32_bf16 v[180:183], v[102:105], v[204:207], v[54:57]
	v_mfma_f32_16x16x32_bf16 v[184:187], v[118:121], v[204:207], v[50:53]
	s_setprio 0
	s_barrier
	s_nop 0
	ds_read_b128 v[50:53], v160 offset:16384
	ds_read_b128 v[54:57], v160 offset:17408
	ds_read_b128 v[86:89], v161 offset:16384
	ds_read_b128 v[200:203], v161 offset:17408
	ds_read_b128 v[204:207], v162 offset:16384
	ds_read_b128 v[208:211], v162 offset:17408
	ds_read_b128 v[212:215], v163 offset:16384
	ds_read_b128 v[216:219], v163 offset:17408
	s_waitcnt vmcnt(4)
	s_barrier
	s_waitcnt lgkmcnt(0)
	s_setprio 1
	s_waitcnt lgkmcnt(0)
	v_mfma_f32_16x16x32_bf16 v[30:33], v[134:137], v[50:53], v[30:33]
	v_mfma_f32_16x16x32_bf16 v[26:29], v[142:145], v[50:53], v[26:29]
	v_mfma_f32_16x16x32_bf16 v[22:25], v[134:137], v[86:89], v[22:25]
	v_mfma_f32_16x16x32_bf16 v[18:21], v[142:145], v[86:89], v[18:21]
	v_mfma_f32_16x16x32_bf16 v[14:17], v[134:137], v[204:207], v[14:17]
	v_mfma_f32_16x16x32_bf16 v[10:13], v[142:145], v[204:207], v[10:13]
	v_mfma_f32_16x16x32_bf16 v[6:9], v[134:137], v[212:215], v[6:9]
	v_mfma_f32_16x16x32_bf16 v[2:5], v[142:145], v[212:215], v[2:5]
	v_mfma_f32_16x16x32_bf16 v[30:33], v[138:141], v[54:57], v[30:33]
	v_mfma_f32_16x16x32_bf16 v[26:29], v[176:179], v[54:57], v[26:29]
	v_mfma_f32_16x16x32_bf16 v[22:25], v[138:141], v[200:203], v[22:25]
	v_mfma_f32_16x16x32_bf16 v[18:21], v[176:179], v[200:203], v[18:21]
	v_mfma_f32_16x16x32_bf16 v[14:17], v[138:141], v[208:211], v[14:17]
	v_mfma_f32_16x16x32_bf16 v[10:13], v[176:179], v[208:211], v[10:13]
	v_mfma_f32_16x16x32_bf16 v[6:9], v[138:141], v[216:219], v[6:9]
	v_mfma_f32_16x16x32_bf16 v[2:5], v[176:179], v[216:219], v[2:5]
	s_setprio 0
	s_setprio 1
	v_mfma_f32_16x16x32_bf16 v[58:61], v[98:101], v[50:53], v[58:61]
	v_mfma_f32_16x16x32_bf16 v[50:53], v[114:117], v[50:53], v[62:65]
	v_mfma_f32_16x16x32_bf16 v[138:141], v[118:121], v[54:57], v[50:53]
	v_mfma_f32_16x16x32_bf16 v[50:53], v[98:101], v[86:89], v[66:69]
	v_mfma_f32_16x16x32_bf16 v[142:145], v[102:105], v[200:203], v[50:53]
	v_mfma_f32_16x16x32_bf16 v[50:53], v[114:117], v[86:89], v[74:77]
	v_mfma_f32_16x16x32_bf16 v[176:179], v[118:121], v[200:203], v[50:53]
	v_mfma_f32_16x16x32_bf16 v[50:53], v[98:101], v[204:207], v[78:81]
	v_mfma_f32_16x16x32_bf16 v[200:203], v[102:105], v[208:211], v[50:53]
	v_mfma_f32_16x16x32_bf16 v[50:53], v[114:117], v[204:207], v[82:85]
	v_mfma_f32_16x16x32_bf16 v[204:207], v[118:121], v[208:211], v[50:53]
	v_mfma_f32_16x16x32_bf16 v[50:53], v[98:101], v[212:215], v[90:93]
	v_mfma_f32_16x16x32_bf16 v[208:211], v[102:105], v[216:219], v[50:53]
	v_mfma_f32_16x16x32_bf16 v[50:53], v[114:117], v[212:215], v[94:97]
	v_mfma_f32_16x16x32_bf16 v[134:137], v[102:105], v[54:57], v[58:61]
	v_mfma_f32_16x16x32_bf16 v[212:215], v[118:121], v[216:219], v[50:53]
	s_setprio 0
	s_barrier
	ds_read_b128 v[74:77], v167
	ds_read_b128 v[216:219], v167 offset:1024
	ds_read_b128 v[220:223], v167 offset:2048
	ds_read_b128 v[244:247], v167 offset:3072
	ds_read_b128 v[58:61], v160 offset:32768
	ds_read_b128 v[62:65], v160 offset:33792
	ds_read_b128 v[66:69], v161 offset:32768
	ds_read_b128 v[78:81], v161 offset:33792
	ds_read_b128 v[94:97], v162 offset:32768
	ds_read_b128 v[248:251], v162 offset:33792
	ds_read_b128 v[188:191], v163 offset:32768
	ds_read_b128 v[146:149], v163 offset:33792
	s_waitcnt vmcnt(2)
	s_barrier
; #define LDA(dst, b, h) for (int m = 0; m < 4; ++m) for (int k = 0; k < 2; ++k) \
;     dst[m][k] = *reinterpret_cast<const bf16x8*>((char*)SA(b, h) + lds_byte(wr * 64 + m * 16 + fr, k * 32 + fq * 8))
; #define LDB(dst, b, h) for (int n = 0; n < 2; ++n) for (int k = 0; k < 2; ++k) \
;     dst[n][k] = *reinterpret_cast<const bf16x8*>((char*)SB(b, h) + lds_byte(wc * 32 + n * 16 + fr, k * 32 + fq * 8))
; #define MMA(ai, bj, At, Bt_) do { __builtin_amdgcn_s_setprio(1); \
;     for (int m = 0; m < 4; ++m) for (int n = 0; n < 2; ++n) for (int k = 0; k < 2; ++k) \
;       acc[ai][bj][m][n] = __builtin_amdgcn_mfma_f32_16x16x32_bf16(Bt_[n][k], At[m][k], acc[ai][bj][m][n], 0, 0, 0); \
;     __builtin_amdgcn_s_setprio(0); } while (0)
; #define WAIT_V(n) asm volatile("s_waitcnt vmcnt(" #n ")" ::: "memory")
; #define WAIT_L(n) asm volatile("s_waitcnt lgkmcnt(" #n ")" ::: "memory")
; #define BAR __builtin_amdgcn_s_barrier()
; template <int EPI> ...
;     ...
;       LDA(At, 0, 1); WAIT_V(4); BAR; WAIT_L(0); MMA(1, 0, At, B0); MMA(1, 1, At, B1); BAR; }
;     { LDB(B0, 1, 0); LDA(At, 1, 0); WAIT_V(2); BAR; WAIT_L(0); MMA(0, 0, At, B0); BAR;
;       LDB(B1, 1, 1); WAIT_V(0); BAR; WAIT_L(0); MMA(0, 1, At, B1); BAR;
;       LDA(At, 1, 1); BAR; WAIT_L(0); MMA(1, 0, At, B0); MMA(1, 1, At, B1); BAR; }
;     if (wr == 0) BAR;
	s_waitcnt lgkmcnt(0)
	s_setprio 1
	s_waitcnt lgkmcnt(0)
	v_mfma_f32_16x16x32_bf16 v[50:53], v[74:77], v[58:61], v[126:129]
	v_mfma_f32_16x16x32_bf16 v[118:121], v[216:219], v[62:65], v[50:53]
	v_mfma_f32_16x16x32_bf16 v[50:53], v[220:223], v[58:61], v[122:125]
	v_mfma_f32_16x16x32_bf16 v[114:117], v[244:247], v[62:65], v[50:53]
	v_mfma_f32_16x16x32_bf16 v[50:53], v[74:77], v[66:69], v[224:227]
	v_mfma_f32_16x16x32_bf16 v[102:105], v[216:219], v[78:81], v[50:53]
	v_mfma_f32_16x16x32_bf16 v[50:53], v[220:223], v[66:69], v[228:231]
	v_mfma_f32_16x16x32_bf16 v[98:101], v[244:247], v[78:81], v[50:53]
	v_mfma_f32_16x16x32_bf16 v[50:53], v[74:77], v[94:97], v[110:113]
	v_mfma_f32_16x16x32_bf16 v[86:89], v[216:219], v[248:251], v[50:53]
	v_mfma_f32_16x16x32_bf16 v[50:53], v[220:223], v[94:97], v[106:109]
	v_mfma_f32_16x16x32_bf16 v[82:85], v[244:247], v[248:251], v[50:53]
	v_mfma_f32_16x16x32_bf16 v[50:53], v[74:77], v[188:191], v[232:235]
	v_mfma_f32_16x16x32_bf16 v[54:57], v[216:219], v[146:149], v[50:53]
	v_mfma_f32_16x16x32_bf16 v[50:53], v[220:223], v[188:191], v[236:239]
	v_mfma_f32_16x16x32_bf16 v[50:53], v[244:247], v[146:149], v[50:53]
	s_setprio 0
	s_barrier
	ds_read_b128 v[224:227], v168
	ds_read_b128 v[228:231], v168 offset:1024
	ds_read_b128 v[232:235], v168 offset:2048
	ds_read_b128 v[236:239], v168 offset:3072
	s_waitcnt vmcnt(0)
	s_barrier
	s_waitcnt lgkmcnt(0)
	s_setprio 1
	s_waitcnt lgkmcnt(0)
	v_mfma_f32_16x16x32_bf16 v[90:93], v[224:227], v[58:61], v[240:243]
	v_mfma_f32_16x16x32_bf16 v[58:61], v[232:235], v[58:61], v[70:73]
	v_mfma_f32_16x16x32_bf16 v[126:129], v[236:239], v[62:65], v[58:61]
	v_mfma_f32_16x16x32_bf16 v[58:61], v[224:227], v[66:69], v[180:183]
	v_mfma_f32_16x16x32_bf16 v[106:109], v[228:231], v[78:81], v[58:61]
	v_mfma_f32_16x16x32_bf16 v[58:61], v[232:235], v[66:69], v[184:187]
	v_mfma_f32_16x16x32_bf16 v[46:49], v[224:227], v[94:97], v[46:49]
	v_mfma_f32_16x16x32_bf16 v[42:45], v[232:235], v[94:97], v[42:45]
	v_mfma_f32_16x16x32_bf16 v[38:41], v[224:227], v[188:191], v[38:41]
	v_mfma_f32_16x16x32_bf16 v[34:37], v[232:235], v[188:191], v[34:37]
	v_mfma_f32_16x16x32_bf16 v[122:125], v[228:231], v[62:65], v[90:93]
	v_mfma_f32_16x16x32_bf16 v[110:113], v[236:239], v[78:81], v[58:61]
	v_mfma_f32_16x16x32_bf16 v[90:93], v[228:231], v[248:251], v[46:49]
	v_mfma_f32_16x16x32_bf16 v[94:97], v[236:239], v[248:251], v[42:45]
	v_mfma_f32_16x16x32_bf16 v[58:61], v[228:231], v[146:149], v[38:41]
	v_mfma_f32_16x16x32_bf16 v[62:65], v[236:239], v[146:149], v[34:37]
	s_setprio 0
	s_barrier
	ds_read_b128 v[38:41], v160 offset:49152
	ds_read_b128 v[42:45], v160 offset:50176
	ds_read_b128 v[146:149], v161 offset:49152
	ds_read_b128 v[180:183], v161 offset:50176
	ds_read_b128 v[184:187], v162 offset:49152
	ds_read_b128 v[188:191], v162 offset:50176
	ds_read_b128 v[240:243], v163 offset:49152
	ds_read_b128 v[248:251], v163 offset:50176
	s_barrier
	s_waitcnt lgkmcnt(0)
	s_setprio 1
	s_waitcnt lgkmcnt(0)
	v_mfma_f32_16x16x32_bf16 v[30:33], v[74:77], v[38:41], v[30:33]
	v_mfma_f32_16x16x32_bf16 v[26:29], v[220:223], v[38:41], v[26:29]
	v_mfma_f32_16x16x32_bf16 v[22:25], v[74:77], v[146:149], v[22:25]
	v_mfma_f32_16x16x32_bf16 v[18:21], v[220:223], v[146:149], v[18:21]
	v_mfma_f32_16x16x32_bf16 v[14:17], v[74:77], v[184:187], v[14:17]
	v_mfma_f32_16x16x32_bf16 v[10:13], v[220:223], v[184:187], v[10:13]
	v_mfma_f32_16x16x32_bf16 v[6:9], v[74:77], v[240:243], v[6:9]
	v_mfma_f32_16x16x32_bf16 v[2:5], v[220:223], v[240:243], v[2:5]
	v_mfma_f32_16x16x32_bf16 v[78:81], v[216:219], v[42:45], v[30:33]
	v_mfma_f32_16x16x32_bf16 v[66:69], v[244:247], v[42:45], v[26:29]
	v_mfma_f32_16x16x32_bf16 v[46:49], v[216:219], v[180:183], v[22:25]
	v_mfma_f32_16x16x32_bf16 v[34:37], v[244:247], v[180:183], v[18:21]
	v_mfma_f32_16x16x32_bf16 v[30:33], v[216:219], v[188:191], v[14:17]
	v_mfma_f32_16x16x32_bf16 v[18:21], v[244:247], v[188:191], v[10:13]
	v_mfma_f32_16x16x32_bf16 v[6:9], v[216:219], v[248:251], v[6:9]
	v_mfma_f32_16x16x32_bf16 v[2:5], v[244:247], v[248:251], v[2:5]
	s_setprio 0
	s_setprio 1
	v_mfma_f32_16x16x32_bf16 v[10:13], v[224:227], v[38:41], v[134:137]
	v_mfma_f32_16x16x32_bf16 v[70:73], v[228:231], v[42:45], v[10:13]
	v_mfma_f32_16x16x32_bf16 v[10:13], v[232:235], v[38:41], v[138:141]
	v_mfma_f32_16x16x32_bf16 v[74:77], v[236:239], v[42:45], v[10:13]
	v_mfma_f32_16x16x32_bf16 v[10:13], v[224:227], v[146:149], v[142:145]
	v_mfma_f32_16x16x32_bf16 v[38:41], v[228:231], v[180:183], v[10:13]
	v_mfma_f32_16x16x32_bf16 v[10:13], v[232:235], v[146:149], v[176:179]
	v_mfma_f32_16x16x32_bf16 v[42:45], v[236:239], v[180:183], v[10:13]
	v_mfma_f32_16x16x32_bf16 v[10:13], v[224:227], v[184:187], v[200:203]
	v_mfma_f32_16x16x32_bf16 v[22:25], v[228:231], v[188:191], v[10:13]
	v_mfma_f32_16x16x32_bf16 v[10:13], v[232:235], v[184:187], v[204:207]
	v_mfma_f32_16x16x32_bf16 v[26:29], v[236:239], v[188:191], v[10:13]
	v_mfma_f32_16x16x32_bf16 v[10:13], v[224:227], v[240:243], v[208:211]
	v_mfma_f32_16x16x32_bf16 v[14:17], v[228:231], v[248:251], v[10:13]
	v_mfma_f32_16x16x32_bf16 v[10:13], v[232:235], v[240:243], v[212:215]
	v_mfma_f32_16x16x32_bf16 v[10:13], v[236:239], v[248:251], v[10:13]
	s_setprio 0
	s_barrier
	s_and_saveexec_b64 s[14:15], s[6:7]
	s_cbranch_execz .LBB0_117
	s_barrier
